# v49 + mode-2 attention: drop the 8 v_mov_b64 negm copies per 2-step iteration (step 2 reads -m from v[50:65]; copies moved to the peeled tail)
# speedup vs baseline: 1.0028x; 1.0028x over previous
.LBB0_426:
.LBB0_427:
	s_setprio 0
	s_add_i32 s60, s57, 4
	s_and_b32 s61, s58, 0xf00000
	s_and_b32 s60, s60, 3
	s_lshl_b32 s78, s61, 1
	v_lshl_add_u64 v[138:139], v[128:129], 0, s[78:79]
	s_lshl_b32 s62, s60, 16
	s_mov_b32 s63, s79
	s_add_i32 s61, s59, s27
	v_lshl_add_u64 v[138:139], v[138:139], 0, s[62:63]
	s_mov_b32 m0, s61
	s_waitcnt vmcnt(0)
	s_barrier
	s_setprio 3
	global_load_lds_dwordx4 v[138:139], off
	s_and_b64 vcc, exec, s[40:41]
	s_cbranch_vccnz .LBB0_429
	v_lshl_add_u64 v[138:139], v[124:125], 0, s[78:79]
	s_mul_i32 s40, s60, 0x38000
	s_mov_b32 s41, s79
	v_lshl_add_u64 v[138:139], v[138:139], 0, s[40:41]
	s_add_i32 s40, s59, s5
	s_add_i32 m0, s40, 0x2000
	s_nop 0
	global_load_lds_dwordx4 v[138:139], off
.LBB0_429:
	s_lshl_b32 s40, s60, 15
	v_exp_f32_e32 v137, v82
	v_exp_f32_e32 v162, v83
	v_lshl_add_u64 v[82:83], v[130:131], 0, s[78:79]
	s_lshl_b32 s78, s40, 1
	v_lshl_add_u64 v[82:83], v[82:83], 0, s[78:79]
	v_lshl_add_u64 v[82:83], v[82:83], 0, s[24:25]
	s_add_i32 m0, s61, 0x3000
	v_exp_f32_e32 v163, v84
	global_load_lds_dwordx4 v[82:83], off
	v_exp_f32_e32 v164, v85
	v_exp_f32_e32 v165, v86
	v_exp_f32_e32 v166, v87
	v_exp_f32_e32 v167, v88
	v_exp_f32_e32 v168, v89
	v_exp_f32_e32 v169, v90
	v_exp_f32_e32 v170, v91
	v_exp_f32_e32 v171, v92
	v_exp_f32_e32 v172, v93
	v_exp_f32_e32 v173, v94
	v_exp_f32_e32 v174, v95
	v_exp_f32_e32 v175, v96
	v_exp_f32_e32 v176, v97
	v_add_u32_e32 v158, s53, v134
	ds_read_b128 v[138:141], v158
	v_exp_f32_e32 v177, v66
	v_exp_f32_e32 v178, v67
	v_exp_f32_e32 v179, v68
	v_exp_f32_e32 v180, v69
	v_exp_f32_e32 v181, v70
	v_exp_f32_e32 v182, v71
	v_exp_f32_e32 v183, v72
	v_exp_f32_e32 v184, v73
	s_waitcnt lgkmcnt(0)
	v_mfma_f32_32x32x16_bf16 v[82:97], v[138:141], v[118:121], v[50:65]
	ds_read_b128 v[138:141], v158 offset:2048
	ds_read_b128 v[142:145], v158 offset:4096
	ds_read_b128 v[66:69], v158 offset:6144
	ds_read_b128 v[70:73], v158 offset:8192
	v_exp_f32_e32 v185, v74
	v_add_f32_e32 v74, v137, v162
	v_exp_f32_e32 v186, v75
	v_exp_f32_e32 v187, v76
	s_waitcnt lgkmcnt(0)
	v_mfma_f32_32x32x16_bf16 v[82:97], v[138:141], v[114:117], v[82:97]
	v_exp_f32_e32 v188, v77
	v_exp_f32_e32 v189, v78
	v_exp_f32_e32 v199, v79
	v_exp_f32_e32 v200, v80
	v_exp_f32_e32 v201, v81
	v_mfma_f32_32x32x16_bf16 v[82:97], v[142:145], v[110:113], v[82:97]
	v_mfma_f32_32x32x16_bf16 v[82:97], v[66:69], v[106:109], v[82:97]
	ds_read_b128 v[138:141], v158 offset:512
	ds_read_b128 v[66:69], v158 offset:10240
	ds_read_b128 v[142:145], v158 offset:2560
	ds_read_b128 v[146:149], v158 offset:4608
	ds_read_b128 v[150:153], v158 offset:6656
	ds_read_b128 v[154:157], v158 offset:8704
	s_setprio 2
	ds_read_b128 v[158:161], v158 offset:10752
	v_mfma_f32_32x32x16_bf16 v[82:97], v[70:73], v[102:105], v[82:97]
	v_add_f32_e32 v70, v163, v74
	v_add_f32_e32 v70, v164, v70
	s_waitcnt lgkmcnt(0)
	v_mfma_f32_32x32x16_bf16 v[82:97], v[66:69], v[98:101], v[82:97]
	v_add_f32_e32 v66, v165, v70
	v_add_f32_e32 v66, v166, v66
	v_add_f32_e32 v66, v167, v66
	v_add_f32_e32 v66, v168, v66
	v_add_f32_e32 v66, v169, v66
	v_add_f32_e32 v66, v170, v66
	v_add_f32_e32 v202, v171, v66
	v_mfma_f32_32x32x16_bf16 v[66:81], v[138:141], v[118:121], v[50:65]
	v_add_f32_e32 v138, v172, v202
	v_add_f32_e32 v138, v173, v138
	v_add_f32_e32 v138, v174, v138
	v_add_f32_e32 v138, v175, v138
	v_add_f32_e32 v138, v176, v138
	v_add_f32_e32 v138, v177, v138
	v_add_f32_e32 v138, v178, v138
	v_mfma_f32_32x32x16_bf16 v[66:81], v[142:145], v[114:117], v[66:81]
	v_add_f32_e32 v138, v179, v138
	v_add_f32_e32 v138, v180, v138
	v_add_f32_e32 v138, v181, v138
	v_add_f32_e32 v138, v182, v138
	v_add_f32_e32 v138, v183, v138
	v_add_f32_e32 v138, v184, v138
	v_add_f32_e32 v138, v185, v138
	v_mfma_f32_32x32x16_bf16 v[66:81], v[146:149], v[110:113], v[66:81]
	v_add_f32_e32 v138, v186, v138
	v_add_f32_e32 v138, v187, v138
	v_add_f32_e32 v138, v188, v138
	v_add_f32_e32 v138, v189, v138
	v_add_f32_e32 v138, v199, v138
	v_add_f32_e32 v202, v200, v138
	v_cvt_pk_bf16_f32 v138, v137, v162
	v_mfma_f32_32x32x16_bf16 v[66:81], v[150:153], v[106:109], v[66:81]
	v_cvt_pk_bf16_f32 v139, v163, v164
	v_cvt_pk_bf16_f32 v140, v165, v166
	v_cvt_pk_bf16_f32 v141, v167, v168
	v_cvt_pk_bf16_f32 v142, v169, v170
	v_cvt_pk_bf16_f32 v143, v171, v172
	v_cvt_pk_bf16_f32 v144, v173, v174
	v_cvt_pk_bf16_f32 v145, v175, v176
	v_mfma_f32_32x32x16_bf16 v[66:81], v[154:157], v[102:105], v[66:81]
	v_cvt_pk_bf16_f32 v146, v177, v178
	v_cvt_pk_bf16_f32 v147, v179, v180
	v_cvt_pk_bf16_f32 v148, v181, v182
	v_cvt_pk_bf16_f32 v149, v183, v184
	v_cvt_pk_bf16_f32 v150, v185, v186
	v_cvt_pk_bf16_f32 v151, v187, v188
	v_cvt_pk_bf16_f32 v152, v189, v199
	v_mfma_f32_32x32x16_bf16 v[66:81], v[158:161], v[98:101], v[66:81]
	v_cvt_pk_bf16_f32 v153, v200, v201
	v_add_u32_e32 v137, s56, v133
	ds_read_b64_tr_b16 v[154:155], v137 offset:12288
	ds_read_b64_tr_b16 v[156:157], v137 offset:12800
	ds_read_b64_tr_b16 v[158:159], v137 offset:16384
	s_waitcnt lgkmcnt(1)
	v_mfma_f32_32x32x16_bf16 v[18:33], v[154:157], v[138:141], v[18:33]
	ds_read_b64_tr_b16 v[160:161], v137 offset:16896
	ds_read_b64_tr_b16 v[154:155], v137 offset:13312
	s_waitcnt lgkmcnt(1)
	v_mfma_f32_32x32x16_bf16 v[2:17], v[158:161], v[138:141], v[2:17]
	ds_read_b64_tr_b16 v[156:157], v137 offset:13824
	ds_read_b64_tr_b16 v[138:139], v137 offset:17408
	s_waitcnt lgkmcnt(1)
	v_mfma_f32_32x32x16_bf16 v[18:33], v[154:157], v[142:145], v[18:33]
	ds_read_b64_tr_b16 v[140:141], v137 offset:17920
	ds_read_b64_tr_b16 v[154:155], v137 offset:14336
	s_waitcnt lgkmcnt(1)
	s_setprio 1
	v_mfma_f32_32x32x16_bf16 v[2:17], v[138:141], v[142:145], v[2:17]
	ds_read_b64_tr_b16 v[156:157], v137 offset:14848
	ds_read_b64_tr_b16 v[138:139], v137 offset:15360
	ds_read_b64_tr_b16 v[140:141], v137 offset:15872
	ds_read_b64_tr_b16 v[142:143], v137 offset:18432
	ds_read_b64_tr_b16 v[144:145], v137 offset:18944
	ds_read_b64_tr_b16 v[158:159], v137 offset:19456
	ds_read_b64_tr_b16 v[160:161], v137 offset:19968
	v_max_f32_e32 v137, v67, v67
	s_waitcnt lgkmcnt(6)
	v_mfma_f32_32x32x16_bf16 v[18:33], v[154:157], v[146:149], v[18:33]
	v_max_f32_e32 v154, v83, v83
	v_max_f32_e32 v137, v154, v137
	v_max3_f32 v154, v82, v66, v84
	v_max3_f32 v137, v137, v85, v69
	v_max3_f32 v154, v154, v68, v86
	v_max3_f32 v137, v137, v87, v71
	v_max3_f32 v137, v137, v89, v73
	s_waitcnt lgkmcnt(2)
	v_mfma_f32_32x32x16_bf16 v[2:17], v[142:145], v[146:149], v[2:17]
	v_max3_f32 v142, v154, v70, v88
	v_max3_f32 v142, v142, v72, v90
	v_max3_f32 v137, v137, v91, v75
	v_max3_f32 v142, v142, v74, v92
	v_max3_f32 v137, v137, v93, v77
	v_max3_f32 v142, v142, v76, v94
	v_max3_f32 v137, v137, v95, v79
	v_mfma_f32_32x32x16_bf16 v[18:33], v[138:141], v[150:153], v[18:33]
	v_max3_f32 v138, v142, v78, v96
	v_max3_f32 v137, v137, v97, v81
	v_add_f32_e32 v139, v201, v202
	v_max3_f32 v137, v138, v80, v137
	v_add_f32_e32 v136, v136, v139
	v_cmp_lt_f32_e32 vcc, s33, v137
	s_waitcnt lgkmcnt(0)
	v_mfma_f32_32x32x16_bf16 v[2:17], v[158:161], v[150:153], v[2:17]
	s_cbranch_vccz .LBB0_431
	v_mov_b32_e32 v34, v137
	s_nop 1
	v_permlane32_swap_b32 v137, v34
	s_nop 1
	s_nop 0
	v_max3_f32 v36, v137, v34, 0
	v_exp_f32_e64 v38, -v36
	v_add_f32_e32 v135, v135, v36
	v_xor_b32_e32 v34, 0x80000000, v135
	v_pk_add_f32 v[82:83], v[82:83], v[36:37] op_sel_hi:[1,0] neg_lo:[0,1] neg_hi:[0,1]
	v_pk_add_f32 v[84:85], v[84:85], v[36:37] op_sel_hi:[1,0] neg_lo:[0,1] neg_hi:[0,1]
	v_pk_add_f32 v[86:87], v[86:87], v[36:37] op_sel_hi:[1,0] neg_lo:[0,1] neg_hi:[0,1]
	v_pk_add_f32 v[88:89], v[88:89], v[36:37] op_sel_hi:[1,0] neg_lo:[0,1] neg_hi:[0,1]
	v_pk_add_f32 v[90:91], v[90:91], v[36:37] op_sel_hi:[1,0] neg_lo:[0,1] neg_hi:[0,1]
	v_pk_add_f32 v[92:93], v[92:93], v[36:37] op_sel_hi:[1,0] neg_lo:[0,1] neg_hi:[0,1]
	v_pk_add_f32 v[94:95], v[94:95], v[36:37] op_sel_hi:[1,0] neg_lo:[0,1] neg_hi:[0,1]
	v_pk_add_f32 v[96:97], v[96:97], v[36:37] op_sel_hi:[1,0] neg_lo:[0,1] neg_hi:[0,1]
	v_sub_f32_e32 v81, v81, v36
	v_sub_f32_e32 v80, v80, v36
	v_sub_f32_e32 v79, v79, v36
	v_sub_f32_e32 v78, v78, v36
	v_sub_f32_e32 v77, v77, v36
	v_sub_f32_e32 v76, v76, v36
	v_sub_f32_e32 v75, v75, v36
	v_sub_f32_e32 v74, v74, v36
	v_sub_f32_e32 v73, v73, v36
	v_sub_f32_e32 v72, v72, v36
	v_sub_f32_e32 v71, v71, v36
	v_sub_f32_e32 v70, v70, v36
	v_sub_f32_e32 v69, v69, v36
	v_sub_f32_e32 v68, v68, v36
	v_sub_f32_e32 v67, v67, v36
	v_sub_f32_e32 v66, v66, v36
	v_pk_mul_f32 v[32:33], v[32:33], v[38:39] op_sel_hi:[1,0]
	v_pk_mul_f32 v[30:31], v[30:31], v[38:39] op_sel_hi:[1,0]
	v_pk_mul_f32 v[28:29], v[28:29], v[38:39] op_sel_hi:[1,0]
	v_pk_mul_f32 v[26:27], v[26:27], v[38:39] op_sel_hi:[1,0]
	v_pk_mul_f32 v[24:25], v[24:25], v[38:39] op_sel_hi:[1,0]
	v_pk_mul_f32 v[22:23], v[22:23], v[38:39] op_sel_hi:[1,0]
	v_pk_mul_f32 v[20:21], v[20:21], v[38:39] op_sel_hi:[1,0]
	v_pk_mul_f32 v[18:19], v[18:19], v[38:39] op_sel_hi:[1,0]
	v_pk_mul_f32 v[16:17], v[16:17], v[38:39] op_sel_hi:[1,0]
	v_pk_mul_f32 v[14:15], v[14:15], v[38:39] op_sel_hi:[1,0]
	v_pk_mul_f32 v[12:13], v[12:13], v[38:39] op_sel_hi:[1,0]
	v_pk_mul_f32 v[10:11], v[10:11], v[38:39] op_sel_hi:[1,0]
	v_pk_mul_f32 v[8:9], v[8:9], v[38:39] op_sel_hi:[1,0]
	v_pk_mul_f32 v[6:7], v[6:7], v[38:39] op_sel_hi:[1,0]
	v_pk_mul_f32 v[4:5], v[4:5], v[38:39] op_sel_hi:[1,0]
	v_pk_mul_f32 v[2:3], v[2:3], v[38:39] op_sel_hi:[1,0]
	v_mul_f32_e32 v136, v136, v38
	v_mov_b32_e32 v35, v34
	v_mov_b32_e32 v36, v34
	v_mov_b32_e32 v37, v34
	v_mov_b32_e32 v38, v34
	v_mov_b32_e32 v39, v34
	v_mov_b32_e32 v40, v34
	v_mov_b32_e32 v41, v34
	v_mov_b32_e32 v42, v34
	v_mov_b32_e32 v43, v34
	v_mov_b32_e32 v44, v34
	v_mov_b32_e32 v45, v34
	v_mov_b32_e32 v46, v34
	v_mov_b32_e32 v47, v34
	v_mov_b32_e32 v48, v34
	v_mov_b32_e32 v49, v34
	v_mov_b32_e32 v50, v34
	v_mov_b32_e32 v51, v34
	v_mov_b32_e32 v52, v34
	v_mov_b32_e32 v53, v34
	v_mov_b32_e32 v54, v34
	v_mov_b32_e32 v55, v34
	v_mov_b32_e32 v56, v34
	v_mov_b32_e32 v57, v34
	v_mov_b32_e32 v58, v34
	v_mov_b32_e32 v59, v34
	v_mov_b32_e32 v60, v34
	v_mov_b32_e32 v61, v34
	v_mov_b32_e32 v62, v34
	v_mov_b32_e32 v63, v34
	v_mov_b32_e32 v64, v34
	v_mov_b32_e32 v65, v34

.LBB0_434:
	v_mov_b64_e32 v[34:35], v[50:51]
	v_mov_b64_e32 v[36:37], v[52:53]
	v_mov_b64_e32 v[38:39], v[54:55]
	v_mov_b64_e32 v[40:41], v[56:57]
	v_mov_b64_e32 v[42:43], v[58:59]
	v_mov_b64_e32 v[44:45], v[60:61]
	v_mov_b64_e32 v[46:47], v[62:63]
	v_mov_b64_e32 v[48:49], v[64:65]
	v_add_u32_e32 v90, s59, v134
	ds_read_b128 v[82:85], v90
	v_exp_f32_e32 v94, v66
	v_exp_f32_e32 v95, v67
	v_exp_f32_e32 v96, v68
	v_exp_f32_e32 v97, v69
	v_exp_f32_e32 v130, v70
	v_exp_f32_e32 v131, v71
	v_exp_f32_e32 v134, v72
	v_exp_f32_e32 v135, v73
	s_waitcnt lgkmcnt(0)
	v_mfma_f32_32x32x16_bf16 v[50:65], v[82:85], v[118:121], v[34:49]
	ds_read_b128 v[82:85], v90 offset:2048
	ds_read_b128 v[86:89], v90 offset:4096
	ds_read_b128 v[66:69], v90 offset:6144
	ds_read_b128 v[70:73], v90 offset:8192
	v_exp_f32_e32 v153, v74
	v_exp_f32_e32 v154, v75
	v_exp_f32_e32 v155, v76
	v_exp_f32_e32 v156, v77
	s_waitcnt lgkmcnt(3)
	v_mfma_f32_32x32x16_bf16 v[50:65], v[82:85], v[114:117], v[50:65]
	v_exp_f32_e32 v157, v78
	v_exp_f32_e32 v158, v79
	v_exp_f32_e32 v159, v80
	v_exp_f32_e32 v160, v81
	v_add_f32_e32 v161, v141, v146
	v_add_f32_e32 v161, v138, v161
	v_add_f32_e32 v161, v142, v161
	s_waitcnt lgkmcnt(2)
	v_mfma_f32_32x32x16_bf16 v[50:65], v[86:89], v[110:113], v[50:65]
	s_waitcnt lgkmcnt(1)
	v_mfma_f32_32x32x16_bf16 v[50:65], v[66:69], v[106:109], v[50:65]
	ds_read_b128 v[66:69], v90 offset:512
	ds_read_b128 v[74:77], v90 offset:10240
	s_waitcnt lgkmcnt(1)
	v_mfma_f32_32x32x16_bf16 v[34:49], v[66:69], v[118:121], v[34:49]
	v_cvt_pk_bf16_f32 v68, v143, v147
	v_cvt_pk_bf16_f32 v67, v138, v142
	v_cvt_pk_bf16_f32 v69, v148, v151
	v_mfma_f32_32x32x16_bf16 v[50:65], v[70:73], v[102:105], v[50:65]
	ds_read_b128 v[70:73], v90 offset:2560
	ds_read_b128 v[78:81], v90 offset:4608
	ds_read_b128 v[82:85], v90 offset:6656
	ds_read_b128 v[86:89], v90 offset:8704
	ds_read_b128 v[90:93], v90 offset:10752
	s_waitcnt lgkmcnt(4)
	v_mfma_f32_32x32x16_bf16 v[34:49], v[70:73], v[114:117], v[34:49]
	v_cvt_pk_bf16_f32 v70, v137, v139
	v_cvt_pk_bf16_f32 v71, v140, v144
	v_cvt_pk_bf16_f32 v72, v145, v149
	v_cvt_pk_bf16_f32 v73, v150, v152
	s_waitcnt lgkmcnt(3)
	v_mfma_f32_32x32x16_bf16 v[34:49], v[78:81], v[110:113], v[34:49]
	v_cvt_pk_bf16_f32 v78, v153, v154
	v_cvt_pk_bf16_f32 v79, v155, v156
	v_cvt_pk_bf16_f32 v80, v157, v158
	v_cvt_pk_bf16_f32 v81, v159, v160
	v_mfma_f32_32x32x16_bf16 v[50:65], v[74:77], v[98:101], v[50:65]
	v_add_f32_e32 v74, v143, v161
	v_add_f32_e32 v74, v147, v74
	v_add_f32_e32 v74, v148, v74
	v_add_f32_e32 v74, v151, v74
	v_add_f32_e32 v74, v137, v74
	v_add_f32_e32 v74, v139, v74
	v_add_f32_e32 v74, v140, v74
	s_waitcnt lgkmcnt(2)
	v_mfma_f32_32x32x16_bf16 v[34:49], v[82:85], v[106:109], v[34:49]
	v_add_f32_e32 v66, v144, v74
	v_add_f32_e32 v66, v145, v66
	v_add_f32_e32 v66, v149, v66
	v_add_f32_e32 v66, v150, v66
	v_add_f32_e32 v66, v152, v66
	v_add_f32_e32 v66, v94, v66
	v_add_f32_e32 v66, v95, v66
	s_waitcnt lgkmcnt(1)
	v_mfma_f32_32x32x16_bf16 v[34:49], v[86:89], v[102:105], v[34:49]
	v_add_f32_e32 v66, v96, v66
	v_add_f32_e32 v66, v97, v66
	v_add_f32_e32 v66, v130, v66
	v_add_f32_e32 v66, v131, v66
	v_add_f32_e32 v66, v134, v66
	v_add_f32_e32 v66, v135, v66
	v_add_f32_e32 v66, v153, v66
	s_waitcnt lgkmcnt(0)
	v_mfma_f32_32x32x16_bf16 v[34:49], v[90:93], v[98:101], v[34:49]
	v_add_f32_e32 v66, v154, v66
	v_add_f32_e32 v66, v155, v66
	v_add_f32_e32 v66, v156, v66
	v_add_f32_e32 v66, v157, v66
	v_add_f32_e32 v66, v158, v66
	v_add_f32_e32 v110, v159, v66
	v_cvt_pk_bf16_f32 v66, v141, v146
	v_cvt_pk_bf16_f32 v74, v94, v95
	v_cvt_pk_bf16_f32 v75, v96, v97
	v_cvt_pk_bf16_f32 v76, v130, v131
	v_cvt_pk_bf16_f32 v77, v134, v135
	v_add_u32_e32 v90, s53, v133
	ds_read_b64_tr_b16 v[82:83], v90 offset:12288
	ds_read_b64_tr_b16 v[84:85], v90 offset:12800
	ds_read_b64_tr_b16 v[86:87], v90 offset:16384
	s_waitcnt lgkmcnt(1)
	v_mfma_f32_32x32x16_bf16 v[18:33], v[82:85], v[66:69], v[18:33]
	ds_read_b64_tr_b16 v[88:89], v90 offset:16896
	ds_read_b64_tr_b16 v[82:83], v90 offset:13312
	s_waitcnt lgkmcnt(1)
	v_mfma_f32_32x32x16_bf16 v[2:17], v[86:89], v[66:69], v[2:17]
	ds_read_b64_tr_b16 v[84:85], v90 offset:13824
	ds_read_b64_tr_b16 v[66:67], v90 offset:17408
	s_waitcnt lgkmcnt(1)
	v_mfma_f32_32x32x16_bf16 v[18:33], v[82:85], v[70:73], v[18:33]
	ds_read_b64_tr_b16 v[68:69], v90 offset:17920
	ds_read_b64_tr_b16 v[82:83], v90 offset:14336
	s_waitcnt lgkmcnt(1)
	v_mfma_f32_32x32x16_bf16 v[2:17], v[66:69], v[70:73], v[2:17]
	ds_read_b64_tr_b16 v[84:85], v90 offset:14848
	ds_read_b64_tr_b16 v[66:67], v90 offset:15360
	ds_read_b64_tr_b16 v[68:69], v90 offset:15872
	ds_read_b64_tr_b16 v[70:71], v90 offset:18432
	ds_read_b64_tr_b16 v[72:73], v90 offset:18944
	ds_read_b64_tr_b16 v[86:87], v90 offset:19456
	ds_read_b64_tr_b16 v[88:89], v90 offset:19968
	s_waitcnt lgkmcnt(6)
	v_mfma_f32_32x32x16_bf16 v[18:33], v[82:85], v[74:77], v[18:33]
	v_max_f32_e32 v82, v35, v35
	v_max_f32_e32 v83, v51, v51
	v_max_f32_e32 v82, v83, v82
	v_max3_f32 v83, v50, v34, v52
	v_max3_f32 v82, v82, v53, v37
	v_max3_f32 v83, v83, v36, v54
	v_max3_f32 v82, v82, v55, v39
	s_waitcnt lgkmcnt(2)
	v_mfma_f32_32x32x16_bf16 v[2:17], v[70:73], v[74:77], v[2:17]
	v_max3_f32 v70, v83, v38, v56
	v_max3_f32 v71, v82, v57, v41
	v_max3_f32 v70, v70, v40, v58
	v_max3_f32 v71, v71, v59, v43
	v_max3_f32 v70, v70, v42, v60
	v_max3_f32 v71, v71, v61, v45
	v_max3_f32 v70, v70, v44, v62
	v_mfma_f32_32x32x16_bf16 v[18:33], v[66:69], v[78:81], v[18:33]
	v_max3_f32 v66, v71, v63, v47
	v_max3_f32 v67, v70, v46, v64
	v_max3_f32 v66, v66, v65, v49
	v_add_f32_e32 v68, v160, v110
	v_max3_f32 v66, v67, v48, v66
	v_add_f32_e32 v68, v136, v68
	v_cmp_lt_f32_e32 vcc, s33, v66
	s_waitcnt lgkmcnt(0)
	v_mfma_f32_32x32x16_bf16 v[2:17], v[86:89], v[78:81], v[2:17]
	s_cbranch_vccz .LBB0_436
	v_mov_b32_e32 v67, v66
	s_nop 1
	v_permlane32_swap_b32 v66, v67
	s_nop 1
	s_nop 0
	v_max3_f32 v66, v66, v67, 0
	v_exp_f32_e64 v70, -v66
	v_pk_add_f32 v[50:51], v[50:51], v[66:67] op_sel_hi:[1,0] neg_lo:[0,1] neg_hi:[0,1]
	v_pk_add_f32 v[52:53], v[52:53], v[66:67] op_sel_hi:[1,0] neg_lo:[0,1] neg_hi:[0,1]
	v_pk_add_f32 v[54:55], v[54:55], v[66:67] op_sel_hi:[1,0] neg_lo:[0,1] neg_hi:[0,1]
	v_pk_add_f32 v[56:57], v[56:57], v[66:67] op_sel_hi:[1,0] neg_lo:[0,1] neg_hi:[0,1]
	v_pk_add_f32 v[58:59], v[58:59], v[66:67] op_sel_hi:[1,0] neg_lo:[0,1] neg_hi:[0,1]
	v_pk_add_f32 v[60:61], v[60:61], v[66:67] op_sel_hi:[1,0] neg_lo:[0,1] neg_hi:[0,1]
	v_pk_add_f32 v[62:63], v[62:63], v[66:67] op_sel_hi:[1,0] neg_lo:[0,1] neg_hi:[0,1]
	v_pk_add_f32 v[64:65], v[64:65], v[66:67] op_sel_hi:[1,0] neg_lo:[0,1] neg_hi:[0,1]
	v_sub_f32_e32 v49, v49, v66
	v_sub_f32_e32 v48, v48, v66
	v_sub_f32_e32 v47, v47, v66
	v_sub_f32_e32 v46, v46, v66
	v_sub_f32_e32 v45, v45, v66
	v_sub_f32_e32 v44, v44, v66
	v_sub_f32_e32 v43, v43, v66
	v_sub_f32_e32 v42, v42, v66
	v_sub_f32_e32 v41, v41, v66
	v_sub_f32_e32 v40, v40, v66
	v_sub_f32_e32 v39, v39, v66
	v_sub_f32_e32 v38, v38, v66
	v_sub_f32_e32 v37, v37, v66
	v_sub_f32_e32 v36, v36, v66
	v_sub_f32_e32 v35, v35, v66
	v_sub_f32_e32 v34, v34, v66
	v_pk_mul_f32 v[32:33], v[32:33], v[70:71] op_sel_hi:[1,0]
	v_pk_mul_f32 v[30:31], v[30:31], v[70:71] op_sel_hi:[1,0]
	v_pk_mul_f32 v[28:29], v[28:29], v[70:71] op_sel_hi:[1,0]
	v_pk_mul_f32 v[26:27], v[26:27], v[70:71] op_sel_hi:[1,0]
	v_pk_mul_f32 v[24:25], v[24:25], v[70:71] op_sel_hi:[1,0]
	v_pk_mul_f32 v[22:23], v[22:23], v[70:71] op_sel_hi:[1,0]
	v_pk_mul_f32 v[20:21], v[20:21], v[70:71] op_sel_hi:[1,0]
	v_pk_mul_f32 v[18:19], v[18:19], v[70:71] op_sel_hi:[1,0]
	v_pk_mul_f32 v[16:17], v[16:17], v[70:71] op_sel_hi:[1,0]
	v_pk_mul_f32 v[14:15], v[14:15], v[70:71] op_sel_hi:[1,0]
	v_pk_mul_f32 v[12:13], v[12:13], v[70:71] op_sel_hi:[1,0]
	v_pk_mul_f32 v[10:11], v[10:11], v[70:71] op_sel_hi:[1,0]
	v_pk_mul_f32 v[8:9], v[8:9], v[70:71] op_sel_hi:[1,0]
	v_pk_mul_f32 v[6:7], v[6:7], v[70:71] op_sel_hi:[1,0]
	v_pk_mul_f32 v[4:5], v[4:5], v[70:71] op_sel_hi:[1,0]
	v_pk_mul_f32 v[2:3], v[2:3], v[70:71] op_sel_hi:[1,0]
	v_mul_f32_e32 v68, v68, v70
